# top-k scoring groups: first MFMA waits vmcnt(7) (first key fragment only) instead of vmcnt(0), so hipcc's counted ladder becomes effective
# speedup vs baseline: 1.0543x; 1.0013x over previous
.LBB0_81:
	v_lshl_add_u64 v[0:1], v[50:51], 0, s[30:31]
	global_load_dwordx4 v[44:47], v[0:1], off offset:-128
	global_load_dwordx4 v[40:43], v[0:1], off offset:-96
	global_load_dwordx4 v[36:39], v[0:1], off offset:-64
	global_load_dwordx4 v[32:35], v[0:1], off offset:-32
	global_load_dwordx4 v[28:31], v[0:1], off
	global_load_dwordx4 v[24:27], v[0:1], off offset:32
	global_load_dwordx4 v[20:23], v[0:1], off offset:64
	global_load_dwordx4 v[16:19], v[0:1], off offset:96
	s_nop 0
	global_load_dwordx4 v[0:3], v[70:71], off
	global_load_dwordx4 v[52:55], v[70:71], off offset:32
	global_load_dwordx4 v[56:59], v[70:71], off offset:64
	global_load_dwordx4 v[60:63], v[70:71], off offset:96
	global_load_dwordx4 v[64:67], v[70:71], off offset:128
	global_load_dwordx4 v[138:141], v[70:71], off offset:160
	global_load_dwordx4 v[142:145], v[70:71], off offset:192
	global_load_dwordx4 v[146:149], v[70:71], off offset:224
	s_waitcnt vmcnt(7)
	v_mfma_f32_32x32x16_bf16 v[0:15], v[44:47], v[0:3], 0
	v_add_u32_e32 v127, 0x400, v209
	v_add_u32_e32 v131, 0x1000, v209
	v_add_u32_e32 v150, 0x1400, v209
	v_add_u32_e32 v151, 0x2000, v209
	v_add_u32_e32 v152, 0x2400, v209
	v_add_u32_e32 v153, 0x3000, v209
	v_add_u32_e32 v154, 0x3400, v209
	s_waitcnt vmcnt(6)
	v_mfma_f32_32x32x16_bf16 v[0:15], v[40:43], v[52:55], v[0:15]
	s_waitcnt vmcnt(5)
	v_mfma_f32_32x32x16_bf16 v[0:15], v[36:39], v[56:59], v[0:15]
	s_waitcnt vmcnt(4)
	v_mfma_f32_32x32x16_bf16 v[0:15], v[32:35], v[60:63], v[0:15]
	s_waitcnt vmcnt(3)
	v_mfma_f32_32x32x16_bf16 v[0:15], v[28:31], v[64:67], v[0:15]
	s_waitcnt vmcnt(2)
	v_mfma_f32_32x32x16_bf16 v[0:15], v[24:27], v[138:141], v[0:15]
	s_waitcnt vmcnt(1)
	v_mfma_f32_32x32x16_bf16 v[0:15], v[20:23], v[142:145], v[0:15]
	s_waitcnt vmcnt(0)
	v_mfma_f32_32x32x16_bf16 v[0:15], v[16:19], v[146:149], v[0:15]
	s_nop 11
	ds_write2_b32 v209, v0, v1 offset1:130
	ds_write2_b32 v127, v2, v3 offset0:4 offset1:134
	ds_write2_b32 v131, v4, v5 offset0:16 offset1:146
	ds_write2_b32 v150, v6, v7 offset0:20 offset1:150
	ds_write2_b32 v151, v8, v9 offset0:32 offset1:162
	ds_write2_b32 v152, v10, v11 offset0:36 offset1:166
	ds_write2_b32 v153, v12, v13 offset0:48 offset1:178
	ds_write2_b32 v154, v14, v15 offset0:52 offset1:182
	global_load_dwordx4 v[0:3], v[78:79], off
	global_load_dwordx4 v[52:55], v[80:81], off
	global_load_dwordx4 v[56:59], v[82:83], off
	global_load_dwordx4 v[60:63], v[84:85], off
	global_load_dwordx4 v[64:67], v[86:87], off
	global_load_dwordx4 v[138:141], v[88:89], off
	global_load_dwordx4 v[142:145], v[90:91], off
	global_load_dwordx4 v[146:149], v[92:93], off
	s_waitcnt vmcnt(7)
	v_mfma_f32_32x32x16_bf16 v[0:15], v[44:47], v[0:3], 0
	s_waitcnt vmcnt(6)
	v_mfma_f32_32x32x16_bf16 v[0:15], v[40:43], v[52:55], v[0:15]
	s_waitcnt vmcnt(5)
	v_mfma_f32_32x32x16_bf16 v[0:15], v[36:39], v[56:59], v[0:15]
	s_waitcnt vmcnt(4)
	v_mfma_f32_32x32x16_bf16 v[0:15], v[32:35], v[60:63], v[0:15]
	s_waitcnt vmcnt(3)
	v_mfma_f32_32x32x16_bf16 v[0:15], v[28:31], v[64:67], v[0:15]
	s_waitcnt vmcnt(2)
	v_mfma_f32_32x32x16_bf16 v[0:15], v[24:27], v[138:141], v[0:15]
	s_waitcnt vmcnt(1)
	v_mfma_f32_32x32x16_bf16 v[0:15], v[20:23], v[142:145], v[0:15]
	s_waitcnt vmcnt(0)
	v_mfma_f32_32x32x16_bf16 v[0:15], v[16:19], v[146:149], v[0:15]
	s_nop 11
	ds_write2_b32 v209, v0, v1 offset0:32 offset1:162
	ds_write2_b32 v127, v2, v3 offset0:36 offset1:166
	ds_write2_b32 v131, v4, v5 offset0:48 offset1:178
	ds_write2_b32 v150, v6, v7 offset0:52 offset1:182
	ds_write2_b32 v151, v8, v9 offset0:64 offset1:194
	ds_write2_b32 v152, v10, v11 offset0:68 offset1:198
	ds_write2_b32 v153, v12, v13 offset0:80 offset1:210
	ds_write2_b32 v154, v14, v15 offset0:84 offset1:214
	global_load_dwordx4 v[0:3], v[94:95], off
	global_load_dwordx4 v[52:55], v[96:97], off
	global_load_dwordx4 v[56:59], v[98:99], off
	global_load_dwordx4 v[60:63], v[100:101], off
	global_load_dwordx4 v[64:67], v[102:103], off
	global_load_dwordx4 v[138:141], v[104:105], off
	global_load_dwordx4 v[142:145], v[106:107], off
	global_load_dwordx4 v[146:149], v[108:109], off
	s_waitcnt vmcnt(7)
	v_mfma_f32_32x32x16_bf16 v[0:15], v[44:47], v[0:3], 0
	s_waitcnt vmcnt(6)
	v_mfma_f32_32x32x16_bf16 v[0:15], v[40:43], v[52:55], v[0:15]
	s_waitcnt vmcnt(5)
	v_mfma_f32_32x32x16_bf16 v[0:15], v[36:39], v[56:59], v[0:15]
	s_waitcnt vmcnt(4)
	v_mfma_f32_32x32x16_bf16 v[0:15], v[32:35], v[60:63], v[0:15]
	s_waitcnt vmcnt(3)
	v_mfma_f32_32x32x16_bf16 v[0:15], v[28:31], v[64:67], v[0:15]
	s_waitcnt vmcnt(2)
	v_mfma_f32_32x32x16_bf16 v[0:15], v[24:27], v[138:141], v[0:15]
	s_waitcnt vmcnt(1)
	v_mfma_f32_32x32x16_bf16 v[0:15], v[20:23], v[142:145], v[0:15]
	s_waitcnt vmcnt(0)
	v_mfma_f32_32x32x16_bf16 v[0:15], v[16:19], v[146:149], v[0:15]
	s_nop 11
	ds_write2_b32 v209, v0, v1 offset0:65 offset1:195
	ds_write2_b32 v127, v2, v3 offset0:69 offset1:199
	ds_write2_b32 v131, v4, v5 offset0:81 offset1:211
	ds_write2_b32 v150, v6, v7 offset0:85 offset1:215
	ds_write2_b32 v151, v8, v9 offset0:97 offset1:227
	ds_write2_b32 v152, v10, v11 offset0:101 offset1:231
	ds_write2_b32 v153, v12, v13 offset0:113 offset1:243
	ds_write2_b32 v154, v14, v15 offset0:117 offset1:247
	global_load_dwordx4 v[0:3], v[110:111], off
	global_load_dwordx4 v[52:55], v[112:113], off
	global_load_dwordx4 v[56:59], v[114:115], off
	global_load_dwordx4 v[60:63], v[116:117], off
	global_load_dwordx4 v[64:67], v[118:119], off
	global_load_dwordx4 v[138:141], v[120:121], off
	global_load_dwordx4 v[142:145], v[122:123], off
	global_load_dwordx4 v[146:149], v[124:125], off
	s_waitcnt vmcnt(7)
	v_mfma_f32_32x32x16_bf16 v[0:15], v[44:47], v[0:3], 0
	s_movk_i32 s0, 0x7f
	s_waitcnt vmcnt(6)
	v_mfma_f32_32x32x16_bf16 v[0:15], v[40:43], v[52:55], v[0:15]
	s_waitcnt vmcnt(5)
	v_mfma_f32_32x32x16_bf16 v[0:15], v[36:39], v[56:59], v[0:15]
	s_waitcnt vmcnt(4)
	v_mfma_f32_32x32x16_bf16 v[0:15], v[32:35], v[60:63], v[0:15]
	s_waitcnt vmcnt(3)
	v_mfma_f32_32x32x16_bf16 v[0:15], v[28:31], v[64:67], v[0:15]
	s_waitcnt vmcnt(2)
	v_mfma_f32_32x32x16_bf16 v[0:15], v[24:27], v[138:141], v[0:15]
	s_waitcnt vmcnt(1)
	v_mfma_f32_32x32x16_bf16 v[0:15], v[20:23], v[142:145], v[0:15]
	v_add_u32_e32 v20, 0x2200, v209
	v_add_u32_e32 v21, 0x2600, v209
	v_add_u32_e32 v22, 0x3200, v209
	v_add_u32_e32 v23, 0x3600, v209
	s_waitcnt vmcnt(0)
	v_mfma_f32_32x32x16_bf16 v[0:15], v[16:19], v[146:149], v[0:15]
	s_nop 11
	ds_write2_b32 v209, v0, v1 offset0:97 offset1:227
	ds_write2_b32 v127, v2, v3 offset0:101 offset1:231
	ds_write2_b32 v131, v4, v5 offset0:113 offset1:243
	ds_write2_b32 v150, v6, v7 offset0:117 offset1:247
	ds_write2_b32 v20, v8, v9 offset0:1 offset1:131
	ds_write2_b32 v21, v10, v11 offset0:5 offset1:135
	ds_write2_b32 v22, v12, v13 offset0:17 offset1:147
	ds_write2_b32 v23, v14, v15 offset0:21 offset1:151
	s_waitcnt lgkmcnt(0)
	s_barrier
	ds_read2_b32 v[0:1], v69 offset1:1
	ds_read2_b32 v[2:3], v69 offset0:2 offset1:3
	ds_read2_b32 v[4:5], v69 offset0:4 offset1:5
	ds_read2_b32 v[6:7], v69 offset0:6 offset1:7
	ds_read2_b32 v[8:9], v69 offset0:8 offset1:9
	ds_read2_b32 v[10:11], v69 offset0:10 offset1:11
	ds_read2_b32 v[12:13], v69 offset0:12 offset1:13
	ds_read2_b32 v[14:15], v69 offset0:14 offset1:15
	s_waitcnt lgkmcnt(7)
	v_cmp_lt_i32_e32 vcc, -1, v0
	s_nop 1
	v_cndmask_b32_e32 v16, -1, v179, vcc
	v_cmp_lt_i32_e32 vcc, -1, v1
	v_bitop3_b32 v0, v16, s97, v0 bitop3:0x48
	s_nop 0
	v_cndmask_b32_e32 v17, -1, v179, vcc
	s_waitcnt lgkmcnt(6)
	v_cmp_lt_i32_e32 vcc, -1, v2
	v_bitop3_b32 v1, v17, s97, v1 bitop3:0x48
	s_nop 0
	v_cndmask_b32_e32 v18, -1, v179, vcc
	v_cmp_lt_i32_e32 vcc, -1, v3
	v_bitop3_b32 v2, v18, s97, v2 bitop3:0x48
	s_nop 0
	v_cndmask_b32_e32 v19, -1, v179, vcc
	s_waitcnt lgkmcnt(5)
	v_cmp_lt_i32_e32 vcc, -1, v4
	v_bitop3_b32 v3, v19, s97, v3 bitop3:0x48
	s_nop 0
	v_cndmask_b32_e32 v20, -1, v179, vcc
	v_cmp_lt_i32_e32 vcc, -1, v5
	v_bitop3_b32 v4, v20, s97, v4 bitop3:0x48
	s_nop 0
	v_cndmask_b32_e32 v21, -1, v179, vcc
	s_waitcnt lgkmcnt(4)
	v_cmp_lt_i32_e32 vcc, -1, v6
	v_bitop3_b32 v5, v21, s97, v5 bitop3:0x48
	s_nop 0
	v_cndmask_b32_e32 v22, -1, v179, vcc
	v_cmp_lt_i32_e32 vcc, -1, v7
	v_bitop3_b32 v6, v22, s97, v6 bitop3:0x48
	s_nop 0
	v_cndmask_b32_e32 v23, -1, v179, vcc
	s_waitcnt lgkmcnt(3)
	v_cmp_lt_i32_e32 vcc, -1, v8
	v_bitop3_b32 v7, v23, s97, v7 bitop3:0x48
	s_nop 0
	v_cndmask_b32_e32 v24, -1, v179, vcc
	v_bitop3_b32 v8, v24, s97, v8 bitop3:0x48
	v_bitop3_b32 v24, v0, s0, v198 bitop3:0x36
	v_sub_u32_e32 v0, v1, v198
	v_add_u32_e32 v28, 0x7e, v0
	v_sub_u32_e32 v0, v8, v198
	v_cmp_lt_i32_e32 vcc, -1, v9
	v_add_u32_e32 v40, 0x77, v0
	v_sub_u32_e32 v1, v2, v198
	v_cndmask_b32_e32 v0, -1, v179, vcc
	v_bitop3_b32 v0, v0, s97, v9 bitop3:0x48
	v_sub_u32_e32 v0, v0, v198
	s_waitcnt lgkmcnt(2)
	v_cmp_lt_i32_e32 vcc, -1, v10
	v_add_u32_e32 v41, 0x76, v0
	v_sub_u32_e32 v2, v3, v198
	v_cndmask_b32_e32 v0, -1, v179, vcc
	v_bitop3_b32 v0, v0, s97, v10 bitop3:0x48
	v_sub_u32_e32 v0, v0, v198
	v_cmp_lt_i32_e32 vcc, -1, v11
	v_add_u32_e32 v42, 0x75, v0
	v_add_u32_e32 v25, 0x7d, v1
	v_cndmask_b32_e32 v0, -1, v179, vcc
	v_bitop3_b32 v0, v0, s97, v11 bitop3:0x48
	v_sub_u32_e32 v0, v0, v198
	s_waitcnt lgkmcnt(1)
	v_cmp_lt_i32_e32 vcc, -1, v12
	v_add_u32_e32 v43, 0x74, v0
	v_add_u32_e32 v29, 0x7c, v2
	v_cndmask_b32_e32 v0, -1, v179, vcc
	v_bitop3_b32 v0, v0, s97, v12 bitop3:0x48
	v_sub_u32_e32 v0, v0, v198
	v_cmp_lt_i32_e32 vcc, -1, v13
	v_add_u32_e32 v44, 0x73, v0
	v_sub_u32_e32 v3, v4, v198
	v_cndmask_b32_e32 v0, -1, v179, vcc
	v_bitop3_b32 v0, v0, s97, v13 bitop3:0x48
	v_sub_u32_e32 v0, v0, v198
	s_waitcnt lgkmcnt(0)
	v_cmp_lt_i32_e32 vcc, -1, v14
	v_add_u32_e32 v45, 0x72, v0
	v_sub_u32_e32 v4, v5, v198
	v_cndmask_b32_e32 v0, -1, v179, vcc
	v_bitop3_b32 v0, v0, s97, v14 bitop3:0x48
	v_sub_u32_e32 v0, v0, v198
	v_cmp_lt_i32_e32 vcc, -1, v15
	v_add_u32_e32 v46, 0x71, v0
	v_sub_u32_e32 v5, v6, v198
	v_cndmask_b32_e32 v0, -1, v179, vcc
	v_bitop3_b32 v0, v0, s97, v15 bitop3:0x48
	v_sub_u32_e32 v2, v0, v198
	ds_read2_b32 v[0:1], v69 offset0:16 offset1:17
	v_add_u32_e32 v47, 0x70, v2
	v_add_u32_e32 v30, 0x7a, v4
	v_add_u32_e32 v27, 0x79, v5
	ds_read2_b32 v[4:5], v69 offset0:18 offset1:19
	ds_read2_b32 v[10:11], v69 offset0:20 offset1:21
	ds_read2_b32 v[16:17], v69 offset0:22 offset1:23
	s_waitcnt lgkmcnt(3)
	v_cmp_lt_i32_e32 vcc, -1, v0
	v_sub_u32_e32 v6, v7, v198
	v_add_u32_e32 v31, 0x78, v6
	v_cndmask_b32_e32 v2, -1, v179, vcc
	v_bitop3_b32 v0, v2, s97, v0 bitop3:0x48
	v_sub_u32_e32 v0, v0, v198
	v_cmp_lt_i32_e32 vcc, -1, v1
	v_add_u32_e32 v2, 0x6f, v0
	v_add_u32_e32 v26, 0x7b, v3
	v_cndmask_b32_e32 v0, -1, v179, vcc
	v_bitop3_b32 v0, v0, s97, v1 bitop3:0x48
	v_sub_u32_e32 v0, v0, v198
	s_waitcnt lgkmcnt(2)
	v_cmp_lt_i32_e32 vcc, -1, v4
	v_add_u32_e32 v6, 0x6e, v0
	v_max_u32_e32 v144, v2, v6
	v_cndmask_b32_e32 v0, -1, v179, vcc
	v_bitop3_b32 v0, v0, s97, v4 bitop3:0x48
	v_sub_u32_e32 v0, v0, v198
	v_cmp_lt_i32_e32 vcc, -1, v5
	v_add_u32_e32 v8, 0x6d, v0
	v_min_u32_e32 v2, v2, v6
	v_cndmask_b32_e32 v0, -1, v179, vcc
	v_bitop3_b32 v0, v0, s97, v5 bitop3:0x48
	v_sub_u32_e32 v0, v0, v198
	s_waitcnt lgkmcnt(1)
	v_cmp_lt_i32_e32 vcc, -1, v10
	v_add_u32_e32 v12, 0x6c, v0
	v_max_u32_e32 v6, v8, v12
	v_cndmask_b32_e32 v0, -1, v179, vcc
	v_bitop3_b32 v0, v0, s97, v10 bitop3:0x48
	v_sub_u32_e32 v0, v0, v198
	v_cmp_lt_i32_e32 vcc, -1, v11
	v_add_u32_e32 v14, 0x6b, v0
	v_min_u32_e32 v8, v8, v12
	v_cndmask_b32_e32 v0, -1, v179, vcc
	v_bitop3_b32 v0, v0, s97, v11 bitop3:0x48
	v_sub_u32_e32 v0, v0, v198
	s_waitcnt lgkmcnt(0)
	v_cmp_lt_i32_e32 vcc, -1, v16
	v_add_u32_e32 v18, 0x6a, v0
	v_max_u32_e32 v12, v14, v18
	v_cndmask_b32_e32 v0, -1, v179, vcc
	v_bitop3_b32 v0, v0, s97, v16 bitop3:0x48
	v_sub_u32_e32 v0, v0, v198
	v_cmp_lt_i32_e32 vcc, -1, v17
	v_add_u32_e32 v20, 0x69, v0
	v_min_u32_e32 v14, v14, v18
	v_cndmask_b32_e32 v0, -1, v179, vcc
	v_bitop3_b32 v0, v0, s97, v17 bitop3:0x48
	v_sub_u32_e32 v3, v0, v198
	ds_read2_b32 v[0:1], v69 offset0:24 offset1:25
	v_add_u32_e32 v23, 0x68, v3
	ds_read2_b32 v[4:5], v69 offset0:26 offset1:27
	ds_read2_b32 v[10:11], v69 offset0:28 offset1:29
	ds_read2_b32 v[16:17], v69 offset0:30 offset1:31
	v_max_u32_e32 v18, v20, v23
	v_min_u32_e32 v20, v20, v23
	s_waitcnt lgkmcnt(3)
	v_cmp_lt_i32_e32 vcc, -1, v0
	s_nop 1
	v_cndmask_b32_e32 v3, -1, v179, vcc
	v_bitop3_b32 v0, v3, s97, v0 bitop3:0x48
	v_sub_u32_e32 v0, v0, v198
	v_cmp_lt_i32_e32 vcc, -1, v1
	v_add_u32_e32 v52, 0x67, v0
	s_nop 0
	v_cndmask_b32_e32 v0, -1, v179, vcc
	v_bitop3_b32 v0, v0, s97, v1 bitop3:0x48
	v_sub_u32_e32 v0, v0, v198
	s_waitcnt lgkmcnt(2)
	v_cmp_lt_i32_e32 vcc, -1, v4
	v_add_u32_e32 v53, 0x66, v0
	v_max_u32_e32 v23, v52, v53
	v_cndmask_b32_e32 v0, -1, v179, vcc
	v_bitop3_b32 v0, v0, s97, v4 bitop3:0x48
	v_sub_u32_e32 v0, v0, v198
	v_cmp_lt_i32_e32 vcc, -1, v5
	v_add_u32_e32 v54, 0x65, v0
	v_min_u32_e32 v52, v52, v53
	v_cndmask_b32_e32 v0, -1, v179, vcc
	v_bitop3_b32 v0, v0, s97, v5 bitop3:0x48
	v_sub_u32_e32 v0, v0, v198
	s_waitcnt lgkmcnt(1)
	v_cmp_lt_i32_e32 vcc, -1, v10
	v_add_u32_e32 v55, 0x64, v0
	ds_read2_b32 v[4:5], v69 offset0:32 offset1:33
	v_cndmask_b32_e32 v0, -1, v179, vcc
	v_bitop3_b32 v0, v0, s97, v10 bitop3:0x48
	v_sub_u32_e32 v0, v0, v198
	v_cmp_lt_i32_e32 vcc, -1, v11
	v_add_u32_e32 v56, 0x63, v0
	v_max_u32_e32 v53, v54, v55
	v_cndmask_b32_e32 v0, -1, v179, vcc
	v_bitop3_b32 v0, v0, s97, v11 bitop3:0x48
	v_sub_u32_e32 v0, v0, v198
	s_waitcnt lgkmcnt(1)
	v_cmp_lt_i32_e32 vcc, -1, v16
	v_add_u32_e32 v57, 0x62, v0
	v_min_u32_e32 v54, v54, v55
	v_cndmask_b32_e32 v0, -1, v179, vcc
	v_bitop3_b32 v0, v0, s97, v16 bitop3:0x48
	v_sub_u32_e32 v0, v0, v198
	v_cmp_lt_i32_e32 vcc, -1, v17
	v_add_u32_e32 v58, 0x61, v0
	v_max_u32_e32 v55, v56, v57
	v_cndmask_b32_e32 v0, -1, v179, vcc
	v_bitop3_b32 v0, v0, s97, v17 bitop3:0x48
	v_sub_u32_e32 v0, v0, v198
	s_waitcnt lgkmcnt(0)
	v_cmp_lt_i32_e32 vcc, -1, v4
	v_add_u32_e32 v59, 0x60, v0
	ds_read2_b32 v[10:11], v69 offset0:34 offset1:35
	ds_read2_b32 v[16:17], v69 offset0:36 offset1:37
	ds_read2_b32 v[32:33], v69 offset0:38 offset1:39
	v_cndmask_b32_e32 v0, -1, v179, vcc
	v_bitop3_b32 v0, v0, s97, v4 bitop3:0x48
	v_sub_u32_e32 v0, v0, v198
	v_cmp_lt_i32_e32 vcc, -1, v5
	v_add_u32_e32 v1, 0x5f, v0
	v_min_u32_e32 v56, v56, v57
	v_cndmask_b32_e32 v0, -1, v179, vcc
	v_bitop3_b32 v0, v0, s97, v5 bitop3:0x48
	v_sub_u32_e32 v0, v0, v198
	s_waitcnt lgkmcnt(2)
	v_cmp_lt_i32_e32 vcc, -1, v10
	v_add_u32_e32 v4, 0x5e, v0
	v_max_u32_e32 v57, v58, v59
	v_cndmask_b32_e32 v0, -1, v179, vcc
	v_bitop3_b32 v0, v0, s97, v10 bitop3:0x48
	v_sub_u32_e32 v0, v0, v198
	v_cmp_lt_i32_e32 vcc, -1, v11
	v_add_u32_e32 v7, 0x5d, v0
	v_min_u32_e32 v58, v58, v59
	v_cndmask_b32_e32 v0, -1, v179, vcc
	v_bitop3_b32 v0, v0, s97, v11 bitop3:0x48
	v_sub_u32_e32 v0, v0, v198
	s_waitcnt lgkmcnt(1)
	v_cmp_lt_i32_e32 vcc, -1, v16
	v_add_u32_e32 v10, 0x5c, v0
	v_max_u32_e32 v152, v1, v4
	v_cndmask_b32_e32 v0, -1, v179, vcc
	v_bitop3_b32 v0, v0, s97, v16 bitop3:0x48
	v_sub_u32_e32 v0, v0, v198
	v_cmp_lt_i32_e32 vcc, -1, v17
	v_add_u32_e32 v13, 0x5b, v0
	v_min_u32_e32 v1, v1, v4
	v_cndmask_b32_e32 v0, -1, v179, vcc
	v_bitop3_b32 v0, v0, s97, v17 bitop3:0x48
	v_sub_u32_e32 v0, v0, v198
	s_waitcnt lgkmcnt(0)
	v_cmp_lt_i32_e32 vcc, -1, v32
	v_add_u32_e32 v16, 0x5a, v0
	v_max_u32_e32 v4, v7, v10
	v_cndmask_b32_e32 v0, -1, v179, vcc
	v_bitop3_b32 v0, v0, s97, v32 bitop3:0x48
	v_sub_u32_e32 v0, v0, v198
	v_cmp_lt_i32_e32 vcc, -1, v33
	v_add_u32_e32 v19, 0x59, v0
	v_min_u32_e32 v7, v7, v10
	v_cndmask_b32_e32 v0, -1, v179, vcc
	v_bitop3_b32 v0, v0, s97, v33 bitop3:0x48
	ds_read2_b32 v[32:33], v69 offset0:40 offset1:41
	v_sub_u32_e32 v0, v0, v198
	v_add_u32_e32 v22, 0x58, v0
	ds_read2_b32 v[34:35], v69 offset0:42 offset1:43
	ds_read2_b32 v[36:37], v69 offset0:44 offset1:45
	ds_read2_b32 v[38:39], v69 offset0:46 offset1:47
	v_max_u32_e32 v10, v13, v16
	s_waitcnt lgkmcnt(3)
	v_cmp_lt_i32_e32 vcc, -1, v32
	v_min_u32_e32 v13, v13, v16
	v_max_u32_e32 v16, v19, v22
	v_cndmask_b32_e32 v0, -1, v179, vcc
	v_bitop3_b32 v0, v0, s97, v32 bitop3:0x48
	v_sub_u32_e32 v0, v0, v198
	v_cmp_lt_i32_e32 vcc, -1, v33
	v_add_u32_e32 v60, 0x57, v0
	v_min_u32_e32 v19, v19, v22
	v_cndmask_b32_e32 v0, -1, v179, vcc
	v_bitop3_b32 v0, v0, s97, v33 bitop3:0x48
	v_sub_u32_e32 v0, v0, v198
	s_waitcnt lgkmcnt(2)
	v_cmp_lt_i32_e32 vcc, -1, v34
	v_add_u32_e32 v61, 0x56, v0
	ds_read2_b32 v[32:33], v69 offset0:48 offset1:49
	v_cndmask_b32_e32 v0, -1, v179, vcc
	v_bitop3_b32 v0, v0, s97, v34 bitop3:0x48
	v_sub_u32_e32 v0, v0, v198
	v_cmp_lt_i32_e32 vcc, -1, v35
	v_add_u32_e32 v62, 0x55, v0
	v_max_u32_e32 v22, v60, v61
	v_cndmask_b32_e32 v0, -1, v179, vcc
	v_bitop3_b32 v0, v0, s97, v35 bitop3:0x48
	v_sub_u32_e32 v0, v0, v198
	s_waitcnt lgkmcnt(2)
	v_cmp_lt_i32_e32 vcc, -1, v36
	v_add_u32_e32 v63, 0x54, v0
	v_min_u32_e32 v60, v60, v61
	v_cndmask_b32_e32 v0, -1, v179, vcc
	v_bitop3_b32 v0, v0, s97, v36 bitop3:0x48
	v_sub_u32_e32 v0, v0, v198
	v_cmp_lt_i32_e32 vcc, -1, v37
	v_add_u32_e32 v64, 0x53, v0
	v_max_u32_e32 v61, v62, v63
	v_cndmask_b32_e32 v0, -1, v179, vcc
	v_bitop3_b32 v0, v0, s97, v37 bitop3:0x48
	v_sub_u32_e32 v0, v0, v198
	s_waitcnt lgkmcnt(1)
	v_cmp_lt_i32_e32 vcc, -1, v38
	v_add_u32_e32 v65, 0x52, v0
	v_min_u32_e32 v62, v62, v63
	v_cndmask_b32_e32 v0, -1, v179, vcc
	v_bitop3_b32 v0, v0, s97, v38 bitop3:0x48
	v_sub_u32_e32 v0, v0, v198
	v_cmp_lt_i32_e32 vcc, -1, v39
	v_add_u32_e32 v66, 0x51, v0
	v_max_u32_e32 v63, v64, v65
	v_cndmask_b32_e32 v0, -1, v179, vcc
	v_bitop3_b32 v0, v0, s97, v39 bitop3:0x48
	ds_read2_b32 v[34:35], v69 offset0:50 offset1:51
	ds_read2_b32 v[36:37], v69 offset0:52 offset1:53
	ds_read2_b32 v[38:39], v69 offset0:54 offset1:55
	v_sub_u32_e32 v0, v0, v198
	s_waitcnt lgkmcnt(3)
	v_cmp_lt_i32_e32 vcc, -1, v32
	v_add_u32_e32 v67, 0x50, v0
	v_min_u32_e32 v64, v64, v65
	v_cndmask_b32_e32 v0, -1, v179, vcc
	v_cmp_lt_i32_e32 vcc, -1, v33
	v_bitop3_b32 v0, v0, s97, v32 bitop3:0x48
	v_sub_u32_e32 v0, v0, v198
	v_cndmask_b32_e32 v3, -1, v179, vcc
	s_waitcnt lgkmcnt(2)
	v_cmp_lt_i32_e32 vcc, -1, v34
	v_bitop3_b32 v3, v3, s97, v33 bitop3:0x48
	ds_read2_b32 v[32:33], v69 offset0:56 offset1:57
	v_cndmask_b32_e32 v5, -1, v179, vcc
	v_cmp_lt_i32_e32 vcc, -1, v35
	v_bitop3_b32 v5, v5, s97, v34 bitop3:0x48
	v_sub_u32_e32 v3, v3, v198
	v_cndmask_b32_e32 v9, -1, v179, vcc
	s_waitcnt lgkmcnt(2)
	v_cmp_lt_i32_e32 vcc, -1, v36
	v_bitop3_b32 v9, v9, s97, v35 bitop3:0x48
	v_sub_u32_e32 v5, v5, v198
	v_cndmask_b32_e32 v11, -1, v179, vcc
	v_cmp_lt_i32_e32 vcc, -1, v37
	v_bitop3_b32 v11, v11, s97, v36 bitop3:0x48
	v_sub_u32_e32 v9, v9, v198
	v_cndmask_b32_e32 v15, -1, v179, vcc
	s_waitcnt lgkmcnt(1)
	v_cmp_lt_i32_e32 vcc, -1, v38
	v_bitop3_b32 v15, v15, s97, v37 bitop3:0x48
	v_sub_u32_e32 v11, v11, v198
	v_cndmask_b32_e32 v17, -1, v179, vcc
	v_cmp_lt_i32_e32 vcc, -1, v39
	v_bitop3_b32 v17, v17, s97, v38 bitop3:0x48
	v_sub_u32_e32 v15, v15, v198
	v_cndmask_b32_e32 v21, -1, v179, vcc
	v_bitop3_b32 v21, v21, s97, v39 bitop3:0x48
	ds_read2_b32 v[34:35], v69 offset0:58 offset1:59
	ds_read2_b32 v[36:37], v69 offset0:60 offset1:61
	ds_read2_b32 v[38:39], v69 offset0:62 offset1:63
	s_waitcnt lgkmcnt(3)
	v_cmp_lt_i32_e32 vcc, -1, v32
	v_sub_u32_e32 v17, v17, v198
	v_sub_u32_e32 v21, v21, v198
	v_cndmask_b32_e32 v127, -1, v179, vcc
	v_cmp_lt_i32_e32 vcc, -1, v33
	v_bitop3_b32 v32, v127, s97, v32 bitop3:0x48
	v_sub_u32_e32 v32, v32, v198
	v_cndmask_b32_e32 v127, -1, v179, vcc
	s_waitcnt lgkmcnt(2)
	v_cmp_lt_i32_e32 vcc, -1, v34
	v_bitop3_b32 v33, v127, s97, v33 bitop3:0x48
	v_sub_u32_e32 v33, v33, v198
	v_cndmask_b32_e32 v127, -1, v179, vcc
	v_cmp_lt_i32_e32 vcc, -1, v35
	v_bitop3_b32 v34, v127, s97, v34 bitop3:0x48
	v_sub_u32_e32 v34, v34, v198
	v_cndmask_b32_e32 v127, -1, v179, vcc
	s_waitcnt lgkmcnt(1)
	v_cmp_lt_i32_e32 vcc, -1, v36
	v_bitop3_b32 v35, v127, s97, v35 bitop3:0x48
	v_sub_u32_e32 v35, v35, v198
	v_cndmask_b32_e32 v127, -1, v179, vcc
	v_cmp_lt_i32_e32 vcc, -1, v37
	v_bitop3_b32 v36, v127, s97, v36 bitop3:0x48
	v_sub_u32_e32 v36, v36, v198
	v_cndmask_b32_e32 v127, -1, v179, vcc
	s_waitcnt lgkmcnt(0)
	v_cmp_lt_i32_e32 vcc, -1, v38
	v_bitop3_b32 v37, v127, s97, v37 bitop3:0x48
	v_sub_u32_e32 v37, v37, v198
	v_cndmask_b32_e32 v127, -1, v179, vcc
	v_cmp_lt_i32_e32 vcc, -1, v39
	v_bitop3_b32 v38, v127, s97, v38 bitop3:0x48
	v_sub_u32_e32 v38, v38, v198
	v_cndmask_b32_e32 v127, -1, v179, vcc
	v_bitop3_b32 v39, v127, s97, v39 bitop3:0x48
	v_sub_u32_e32 v39, v39, v198
	v_add_u32_e32 v0, 0x4f, v0
	v_add_u32_e32 v3, 0x4e, v3
	v_add_u32_e32 v5, 0x4d, v5
	v_add_u32_e32 v9, 0x4c, v9
	v_add_u32_e32 v11, 0x4b, v11
	v_add_u32_e32 v15, 0x4a, v15
	v_add_u32_e32 v17, 0x49, v17
	v_add_u32_e32 v21, 0x48, v21
	v_add_u32_e32 v32, 0x47, v32
	v_add_u32_e32 v33, 0x46, v33
	v_add_u32_e32 v34, 0x45, v34
	v_add_u32_e32 v35, 0x44, v35
	v_add_u32_e32 v36, 0x43, v36
	v_add_u32_e32 v37, 0x42, v37
	v_add_u32_e32 v38, 0x41, v38
	v_add_u32_e32 v39, 64, v39
	v_max_u32_e32 v127, v24, v28
	v_min_u32_e32 v24, v24, v28
	v_max_u32_e32 v28, v25, v29
	v_min_u32_e32 v25, v25, v29
	v_max_u32_e32 v29, v26, v30
	v_min_u32_e32 v26, v26, v30
	v_max_u32_e32 v30, v27, v31
	v_min_u32_e32 v27, v27, v31
	v_max_u32_e32 v31, v40, v41
	v_min_u32_e32 v40, v40, v41
	v_max_u32_e32 v41, v42, v43
	v_min_u32_e32 v42, v42, v43
	v_max_u32_e32 v43, v44, v45
	v_min_u32_e32 v44, v44, v45
	v_max_u32_e32 v45, v46, v47
	v_min_u32_e32 v46, v46, v47
	v_max_u32_e32 v65, v66, v67
	v_min_u32_e32 v66, v66, v67
	v_max_u32_e32 v160, v0, v3
	v_min_u32_e32 v0, v0, v3
	v_max_u32_e32 v3, v5, v9
	v_min_u32_e32 v5, v5, v9
	v_max_u32_e32 v9, v11, v15
	v_min_u32_e32 v11, v11, v15
	v_max_u32_e32 v15, v17, v21
	v_min_u32_e32 v17, v17, v21
	v_max_u32_e32 v21, v32, v33
	v_min_u32_e32 v32, v32, v33
	v_max_u32_e32 v33, v34, v35
	v_min_u32_e32 v34, v34, v35
	v_max_u32_e32 v35, v36, v37
	v_min_u32_e32 v36, v36, v37
	v_max_u32_e32 v37, v38, v39
	v_min_u32_e32 v38, v38, v39
	v_max_u32_e32 v47, v127, v25
	v_min_u32_e32 v25, v127, v25
	v_max_u32_e32 v127, v24, v28
	v_min_u32_e32 v24, v24, v28
	v_max_u32_e32 v28, v29, v27
	v_min_u32_e32 v27, v29, v27
	v_max_u32_e32 v29, v26, v30
	v_min_u32_e32 v26, v26, v30
	v_max_u32_e32 v30, v31, v42
	v_min_u32_e32 v31, v31, v42
	v_max_u32_e32 v42, v40, v41
	v_min_u32_e32 v40, v40, v41
	v_max_u32_e32 v41, v43, v46
	v_min_u32_e32 v43, v43, v46
	v_max_u32_e32 v46, v44, v45
	v_min_u32_e32 v44, v44, v45
	v_max_u32_e32 v59, v144, v8
	v_min_u32_e32 v8, v144, v8
	v_max_u32_e32 v144, v2, v6
	v_min_u32_e32 v2, v2, v6
	v_max_u32_e32 v6, v12, v20
	v_min_u32_e32 v12, v12, v20
	v_max_u32_e32 v20, v14, v18
	v_min_u32_e32 v14, v14, v18
	v_max_u32_e32 v18, v23, v54
	v_min_u32_e32 v23, v23, v54
	v_max_u32_e32 v54, v52, v53
	v_min_u32_e32 v52, v52, v53
	v_max_u32_e32 v53, v55, v58
	v_min_u32_e32 v55, v55, v58
	v_max_u32_e32 v58, v56, v57
	v_min_u32_e32 v56, v56, v57
	v_max_u32_e32 v67, v152, v7
	v_min_u32_e32 v7, v152, v7
	v_max_u32_e32 v152, v1, v4
	v_min_u32_e32 v1, v1, v4
	v_max_u32_e32 v4, v10, v19
	v_min_u32_e32 v10, v10, v19
	v_max_u32_e32 v19, v13, v16
	v_min_u32_e32 v13, v13, v16
	v_max_u32_e32 v16, v22, v62
	v_min_u32_e32 v22, v22, v62
	v_max_u32_e32 v62, v60, v61
	v_min_u32_e32 v60, v60, v61
	v_max_u32_e32 v61, v63, v66
	v_min_u32_e32 v63, v63, v66
	v_max_u32_e32 v66, v64, v65
	v_min_u32_e32 v64, v64, v65
	v_max_u32_e32 v39, v160, v5
	v_min_u32_e32 v5, v160, v5
	v_max_u32_e32 v160, v0, v3
	v_min_u32_e32 v0, v0, v3
	v_max_u32_e32 v3, v9, v17
	v_min_u32_e32 v9, v9, v17
	v_max_u32_e32 v17, v11, v15
	v_min_u32_e32 v11, v11, v15
	v_max_u32_e32 v15, v21, v34
	v_min_u32_e32 v21, v21, v34
	v_max_u32_e32 v34, v32, v33
	v_min_u32_e32 v32, v32, v33
	v_max_u32_e32 v33, v35, v38
	v_min_u32_e32 v35, v35, v38
	v_max_u32_e32 v38, v36, v37
	v_min_u32_e32 v36, v36, v37
	v_max_u32_e32 v45, v47, v127
	v_min_u32_e32 v47, v47, v127
	v_max_u32_e32 v127, v25, v24
	v_min_u32_e32 v24, v25, v24
	v_max_u32_e32 v25, v27, v26
	v_min_u32_e32 v26, v27, v26
	v_max_u32_e32 v27, v28, v29
	v_min_u32_e32 v28, v28, v29
	v_max_u32_e32 v29, v30, v42
	v_min_u32_e32 v30, v30, v42
	v_max_u32_e32 v42, v31, v40
	v_min_u32_e32 v31, v31, v40
	v_max_u32_e32 v40, v43, v44
	v_min_u32_e32 v43, v43, v44
	v_max_u32_e32 v44, v41, v46
	v_min_u32_e32 v41, v41, v46
	v_max_u32_e32 v57, v59, v144
	v_min_u32_e32 v59, v59, v144
	v_max_u32_e32 v144, v8, v2
	v_min_u32_e32 v2, v8, v2
	v_max_u32_e32 v8, v12, v14
	v_min_u32_e32 v12, v12, v14
	v_max_u32_e32 v14, v6, v20
	v_min_u32_e32 v6, v6, v20
	v_max_u32_e32 v20, v18, v54
	v_min_u32_e32 v18, v18, v54
	v_max_u32_e32 v54, v23, v52
	v_min_u32_e32 v23, v23, v52
	v_max_u32_e32 v52, v55, v56
	v_min_u32_e32 v55, v55, v56
	v_max_u32_e32 v56, v53, v58
	v_min_u32_e32 v53, v53, v58
	v_max_u32_e32 v65, v67, v152
	v_min_u32_e32 v67, v67, v152
	v_max_u32_e32 v152, v7, v1
	v_min_u32_e32 v1, v7, v1
	v_max_u32_e32 v7, v10, v13
	v_min_u32_e32 v10, v10, v13
	v_max_u32_e32 v13, v4, v19
	v_min_u32_e32 v4, v4, v19
	v_max_u32_e32 v19, v16, v62
	v_min_u32_e32 v16, v16, v62
	v_max_u32_e32 v62, v22, v60
	v_min_u32_e32 v22, v22, v60
	v_max_u32_e32 v60, v63, v64
	v_min_u32_e32 v63, v63, v64
	v_max_u32_e32 v64, v61, v66
	v_min_u32_e32 v61, v61, v66
	v_max_u32_e32 v37, v39, v160
	v_min_u32_e32 v39, v39, v160
	v_max_u32_e32 v160, v5, v0
	v_min_u32_e32 v0, v5, v0
	v_max_u32_e32 v5, v9, v11
	v_min_u32_e32 v9, v9, v11
	v_max_u32_e32 v11, v3, v17
	v_min_u32_e32 v3, v3, v17
	v_max_u32_e32 v17, v15, v34
	v_min_u32_e32 v15, v15, v34
	v_max_u32_e32 v34, v21, v32
	v_min_u32_e32 v21, v21, v32
	v_max_u32_e32 v32, v35, v36
	v_min_u32_e32 v35, v35, v36
	v_max_u32_e32 v36, v33, v38
	v_min_u32_e32 v33, v33, v38
	v_max_u32_e32 v46, v45, v26
	v_min_u32_e32 v26, v45, v26
	v_max_u32_e32 v45, v47, v25
	v_min_u32_e32 v25, v47, v25
	v_max_u32_e32 v47, v127, v28
	v_min_u32_e32 v28, v127, v28
	v_max_u32_e32 v127, v24, v27
	v_min_u32_e32 v24, v24, v27
	v_max_u32_e32 v27, v29, v43
	v_min_u32_e32 v29, v29, v43
	v_max_u32_e32 v43, v30, v40
	v_min_u32_e32 v30, v30, v40
	v_max_u32_e32 v40, v42, v41
	v_min_u32_e32 v41, v42, v41
	v_max_u32_e32 v42, v31, v44
	v_min_u32_e32 v31, v31, v44
	v_max_u32_e32 v58, v57, v12
	v_min_u32_e32 v12, v57, v12
	v_max_u32_e32 v57, v59, v8
	v_min_u32_e32 v8, v59, v8
	v_max_u32_e32 v59, v144, v6
	v_min_u32_e32 v6, v144, v6
	v_max_u32_e32 v144, v2, v14
	v_min_u32_e32 v2, v2, v14
	v_max_u32_e32 v14, v20, v55
	v_min_u32_e32 v20, v20, v55
	v_max_u32_e32 v55, v18, v52
	v_min_u32_e32 v18, v18, v52
	v_max_u32_e32 v52, v54, v53
	v_min_u32_e32 v53, v54, v53
	v_max_u32_e32 v54, v23, v56
	v_min_u32_e32 v23, v23, v56
	v_max_u32_e32 v66, v65, v10
	v_min_u32_e32 v10, v65, v10
	v_max_u32_e32 v65, v67, v7
	v_min_u32_e32 v7, v67, v7
	v_max_u32_e32 v67, v152, v4
	v_min_u32_e32 v4, v152, v4
	v_max_u32_e32 v152, v1, v13
	v_min_u32_e32 v1, v1, v13
	v_max_u32_e32 v13, v19, v63
	v_min_u32_e32 v19, v19, v63
	v_max_u32_e32 v63, v16, v60
	v_min_u32_e32 v16, v16, v60
	v_max_u32_e32 v60, v62, v61
	v_min_u32_e32 v61, v62, v61
	v_max_u32_e32 v62, v22, v64
	v_min_u32_e32 v22, v22, v64
	v_max_u32_e32 v38, v37, v9
	v_min_u32_e32 v9, v37, v9
	v_max_u32_e32 v37, v39, v5
	v_min_u32_e32 v5, v39, v5
	v_max_u32_e32 v39, v160, v3
	v_min_u32_e32 v3, v160, v3
	v_max_u32_e32 v160, v0, v11
	v_min_u32_e32 v0, v0, v11
	v_max_u32_e32 v11, v17, v35
	v_min_u32_e32 v17, v17, v35
	v_max_u32_e32 v35, v15, v32
	v_min_u32_e32 v15, v15, v32
	v_max_u32_e32 v32, v34, v33
	v_min_u32_e32 v33, v34, v33
	v_max_u32_e32 v34, v21, v36
	v_min_u32_e32 v21, v21, v36
	v_max_u32_e32 v44, v46, v47
	v_min_u32_e32 v46, v46, v47
	v_max_u32_e32 v47, v45, v127
	v_min_u32_e32 v45, v45, v127
	v_max_u32_e32 v127, v26, v28
	v_min_u32_e32 v26, v26, v28
	v_max_u32_e32 v28, v25, v24
	v_min_u32_e32 v24, v25, v24
	v_max_u32_e32 v25, v29, v41
	v_min_u32_e32 v29, v29, v41
	v_max_u32_e32 v41, v30, v31
	v_min_u32_e32 v30, v30, v31
	v_max_u32_e32 v31, v27, v40
	v_min_u32_e32 v27, v27, v40
	v_max_u32_e32 v40, v43, v42
	v_min_u32_e32 v42, v43, v42
	v_max_u32_e32 v56, v58, v59
	v_min_u32_e32 v58, v58, v59
	v_max_u32_e32 v59, v57, v144
	v_min_u32_e32 v57, v57, v144
	v_max_u32_e32 v144, v12, v6
	v_min_u32_e32 v6, v12, v6
	v_max_u32_e32 v12, v8, v2
	v_min_u32_e32 v2, v8, v2
	v_max_u32_e32 v8, v20, v53
	v_min_u32_e32 v20, v20, v53
	v_max_u32_e32 v53, v18, v23
	v_min_u32_e32 v18, v18, v23
	v_max_u32_e32 v23, v14, v52
	v_min_u32_e32 v14, v14, v52
	v_max_u32_e32 v52, v55, v54
	v_min_u32_e32 v54, v55, v54
	v_max_u32_e32 v64, v66, v67
	v_min_u32_e32 v66, v66, v67
	v_max_u32_e32 v67, v65, v152
	v_min_u32_e32 v65, v65, v152
	v_max_u32_e32 v152, v10, v4
	v_min_u32_e32 v4, v10, v4
	v_max_u32_e32 v10, v7, v1
	v_min_u32_e32 v1, v7, v1
	v_max_u32_e32 v7, v19, v61
	v_min_u32_e32 v19, v19, v61
	v_max_u32_e32 v61, v16, v22
	v_min_u32_e32 v16, v16, v22
	v_max_u32_e32 v22, v13, v60
	v_min_u32_e32 v13, v13, v60
	v_max_u32_e32 v60, v63, v62
	v_min_u32_e32 v62, v63, v62
	v_max_u32_e32 v36, v38, v39
	v_min_u32_e32 v38, v38, v39
	v_max_u32_e32 v39, v37, v160
	v_min_u32_e32 v37, v37, v160
	v_max_u32_e32 v160, v9, v3
	v_min_u32_e32 v3, v9, v3
	v_max_u32_e32 v9, v5, v0
	v_min_u32_e32 v0, v5, v0
	v_max_u32_e32 v5, v17, v33
	v_min_u32_e32 v17, v17, v33
	v_max_u32_e32 v33, v15, v21
	v_min_u32_e32 v15, v15, v21
	v_max_u32_e32 v21, v11, v32
	v_min_u32_e32 v11, v11, v32
	v_max_u32_e32 v32, v35, v34
	v_min_u32_e32 v34, v35, v34
	v_max_u32_e32 v43, v44, v47
	v_min_u32_e32 v44, v44, v47
	v_max_u32_e32 v47, v46, v45
	v_min_u32_e32 v45, v46, v45
	v_max_u32_e32 v46, v127, v28
	v_min_u32_e32 v28, v127, v28
	v_max_u32_e32 v127, v26, v24
	v_min_u32_e32 v24, v26, v24
	v_max_u32_e32 v26, v29, v30
	v_min_u32_e32 v29, v29, v30
	v_max_u32_e32 v30, v25, v41
	v_min_u32_e32 v25, v25, v41
	v_max_u32_e32 v41, v27, v42
	v_min_u32_e32 v27, v27, v42
	v_max_u32_e32 v42, v31, v40
	v_min_u32_e32 v31, v31, v40
	v_max_u32_e32 v55, v56, v59
	v_min_u32_e32 v56, v56, v59
	v_max_u32_e32 v59, v58, v57
	v_min_u32_e32 v57, v58, v57
	v_max_u32_e32 v58, v144, v12
	v_min_u32_e32 v12, v144, v12
	v_max_u32_e32 v144, v6, v2
	v_min_u32_e32 v2, v6, v2
	v_max_u32_e32 v6, v20, v18
	v_min_u32_e32 v18, v20, v18
	v_max_u32_e32 v20, v8, v53
	v_min_u32_e32 v8, v8, v53
	v_max_u32_e32 v53, v14, v54
	v_min_u32_e32 v14, v14, v54
	v_max_u32_e32 v54, v23, v52
	v_min_u32_e32 v23, v23, v52
	v_max_u32_e32 v63, v64, v67
	v_min_u32_e32 v64, v64, v67
	v_max_u32_e32 v67, v66, v65
	v_min_u32_e32 v65, v66, v65
	v_max_u32_e32 v66, v152, v10
	v_min_u32_e32 v10, v152, v10
	v_max_u32_e32 v152, v4, v1
	v_min_u32_e32 v1, v4, v1
	v_max_u32_e32 v4, v19, v16
	v_min_u32_e32 v16, v19, v16
	v_max_u32_e32 v19, v7, v61
	v_min_u32_e32 v7, v7, v61
	v_max_u32_e32 v61, v13, v62
	v_min_u32_e32 v13, v13, v62
	v_max_u32_e32 v62, v22, v60
	v_min_u32_e32 v22, v22, v60
	v_max_u32_e32 v35, v36, v39
	v_min_u32_e32 v36, v36, v39
	v_max_u32_e32 v39, v38, v37
	v_min_u32_e32 v37, v38, v37
	v_max_u32_e32 v38, v160, v9
	v_min_u32_e32 v9, v160, v9
	v_max_u32_e32 v160, v3, v0
	v_min_u32_e32 v0, v3, v0
	v_max_u32_e32 v3, v17, v15
	v_min_u32_e32 v15, v17, v15
	v_max_u32_e32 v17, v5, v33
	v_min_u32_e32 v5, v5, v33
	v_max_u32_e32 v33, v11, v34
	v_min_u32_e32 v11, v11, v34
	v_max_u32_e32 v34, v21, v32
	v_min_u32_e32 v21, v21, v32
	v_max_u32_e32 v40, v43, v29
	v_min_u32_e32 v29, v43, v29
	v_max_u32_e32 v43, v44, v26
	v_min_u32_e32 v26, v44, v26
	v_max_u32_e32 v44, v47, v25
	v_min_u32_e32 v25, v47, v25
	v_max_u32_e32 v47, v45, v30
	v_min_u32_e32 v30, v45, v30
	v_max_u32_e32 v45, v46, v27
	v_min_u32_e32 v27, v46, v27
	v_max_u32_e32 v46, v28, v41
	v_min_u32_e32 v28, v28, v41
	v_max_u32_e32 v41, v127, v31
	v_min_u32_e32 v31, v127, v31
	v_max_u32_e32 v127, v24, v42
	v_min_u32_e32 v24, v24, v42
	v_max_u32_e32 v52, v55, v18
	v_min_u32_e32 v18, v55, v18
	v_max_u32_e32 v55, v56, v6
	v_min_u32_e32 v6, v56, v6
	v_max_u32_e32 v56, v59, v8
	v_min_u32_e32 v8, v59, v8
	v_max_u32_e32 v59, v57, v20
	v_min_u32_e32 v20, v57, v20
	v_max_u32_e32 v57, v58, v14
	v_min_u32_e32 v14, v58, v14
	v_max_u32_e32 v58, v12, v53
	v_min_u32_e32 v12, v12, v53
	v_max_u32_e32 v53, v144, v23
	v_min_u32_e32 v23, v144, v23
	v_max_u32_e32 v144, v2, v54
	v_min_u32_e32 v2, v2, v54
	v_max_u32_e32 v60, v63, v16
	v_min_u32_e32 v16, v63, v16
	v_max_u32_e32 v63, v64, v4
	v_min_u32_e32 v4, v64, v4
	v_max_u32_e32 v64, v67, v7
	v_min_u32_e32 v7, v67, v7
	v_max_u32_e32 v67, v65, v19
	v_min_u32_e32 v19, v65, v19
	v_max_u32_e32 v65, v66, v13
	v_min_u32_e32 v13, v66, v13
	v_max_u32_e32 v66, v10, v61
	v_min_u32_e32 v10, v10, v61
	v_max_u32_e32 v61, v152, v22
	v_min_u32_e32 v22, v152, v22
	v_max_u32_e32 v152, v1, v62
	v_min_u32_e32 v1, v1, v62
	v_max_u32_e32 v32, v35, v15
	v_min_u32_e32 v15, v35, v15
	v_max_u32_e32 v35, v36, v3
	v_min_u32_e32 v3, v36, v3
	v_max_u32_e32 v36, v39, v5
	v_min_u32_e32 v5, v39, v5
	v_max_u32_e32 v39, v37, v17
	v_min_u32_e32 v17, v37, v17
	v_max_u32_e32 v37, v38, v11
	v_min_u32_e32 v11, v38, v11
	v_max_u32_e32 v38, v9, v33
	v_min_u32_e32 v9, v9, v33
	v_max_u32_e32 v33, v160, v21
	v_min_u32_e32 v21, v160, v21
	v_max_u32_e32 v160, v0, v34
	v_min_u32_e32 v0, v0, v34
	v_max_u32_e32 v42, v40, v45
	v_min_u32_e32 v40, v40, v45
	v_max_u32_e32 v45, v43, v46
	v_min_u32_e32 v43, v43, v46
	v_max_u32_e32 v46, v44, v41
	v_min_u32_e32 v41, v44, v41
	v_max_u32_e32 v44, v47, v127
	v_min_u32_e32 v47, v47, v127
	v_max_u32_e32 v127, v29, v27
	v_min_u32_e32 v27, v29, v27
	v_max_u32_e32 v29, v26, v28
	v_min_u32_e32 v26, v26, v28
	v_max_u32_e32 v28, v25, v31
	v_min_u32_e32 v25, v25, v31
	v_max_u32_e32 v31, v30, v24
	v_min_u32_e32 v24, v30, v24
	v_max_u32_e32 v54, v52, v57
	v_min_u32_e32 v52, v52, v57
	v_max_u32_e32 v57, v55, v58
	v_min_u32_e32 v55, v55, v58
	v_max_u32_e32 v58, v56, v53
	v_min_u32_e32 v53, v56, v53
	v_max_u32_e32 v56, v59, v144
	v_min_u32_e32 v59, v59, v144
	v_max_u32_e32 v144, v18, v14
	v_min_u32_e32 v14, v18, v14
	v_max_u32_e32 v18, v6, v12
	v_min_u32_e32 v6, v6, v12
	v_max_u32_e32 v12, v8, v23
	v_min_u32_e32 v8, v8, v23
	v_max_u32_e32 v23, v20, v2
	v_min_u32_e32 v2, v20, v2
	v_max_u32_e32 v62, v60, v65
	v_min_u32_e32 v60, v60, v65
	v_max_u32_e32 v65, v63, v66
	v_min_u32_e32 v63, v63, v66
	v_max_u32_e32 v66, v64, v61
	v_min_u32_e32 v61, v64, v61
	v_max_u32_e32 v64, v67, v152
	v_min_u32_e32 v67, v67, v152
	v_max_u32_e32 v152, v16, v13
	v_min_u32_e32 v13, v16, v13
	v_max_u32_e32 v16, v4, v10
	v_min_u32_e32 v4, v4, v10
	v_max_u32_e32 v10, v7, v22
	v_min_u32_e32 v7, v7, v22
	v_max_u32_e32 v22, v19, v1
	v_min_u32_e32 v1, v19, v1
	v_max_u32_e32 v34, v32, v37
	v_min_u32_e32 v32, v32, v37
	v_max_u32_e32 v37, v35, v38
	v_min_u32_e32 v35, v35, v38
	v_max_u32_e32 v38, v36, v33
	v_min_u32_e32 v33, v36, v33
	v_max_u32_e32 v36, v39, v160
	v_min_u32_e32 v39, v39, v160
	v_max_u32_e32 v160, v15, v11
	v_min_u32_e32 v11, v15, v11
	v_max_u32_e32 v15, v3, v9
	v_min_u32_e32 v3, v3, v9
	v_max_u32_e32 v9, v5, v21
	v_min_u32_e32 v5, v5, v21
	v_max_u32_e32 v21, v17, v0
	v_min_u32_e32 v0, v17, v0
	v_max_u32_e32 v30, v42, v46
	v_min_u32_e32 v42, v42, v46
	v_max_u32_e32 v46, v45, v44
	v_min_u32_e32 v44, v45, v44
	v_max_u32_e32 v45, v40, v41
	v_min_u32_e32 v40, v40, v41
	v_max_u32_e32 v41, v43, v47
	v_min_u32_e32 v43, v43, v47
	v_max_u32_e32 v47, v127, v28
	v_min_u32_e32 v28, v127, v28
	v_max_u32_e32 v127, v29, v31
	v_min_u32_e32 v29, v29, v31
	v_max_u32_e32 v31, v27, v25
	v_min_u32_e32 v25, v27, v25
	v_max_u32_e32 v27, v26, v24
	v_min_u32_e32 v24, v26, v24
	v_max_u32_e32 v20, v54, v58
	v_min_u32_e32 v54, v54, v58
	v_max_u32_e32 v58, v57, v56
	v_min_u32_e32 v56, v57, v56
	v_max_u32_e32 v57, v52, v53
	v_min_u32_e32 v52, v52, v53
	v_max_u32_e32 v53, v55, v59
	v_min_u32_e32 v55, v55, v59
	v_max_u32_e32 v59, v144, v12
	v_min_u32_e32 v12, v144, v12
	v_max_u32_e32 v144, v18, v23
	v_min_u32_e32 v18, v18, v23
	v_max_u32_e32 v23, v14, v8
	v_min_u32_e32 v8, v14, v8
	v_max_u32_e32 v14, v6, v2
	v_min_u32_e32 v2, v6, v2
	v_max_u32_e32 v19, v62, v66
	v_min_u32_e32 v62, v62, v66
	v_max_u32_e32 v66, v65, v64
	v_min_u32_e32 v64, v65, v64
	v_max_u32_e32 v65, v60, v61
	v_min_u32_e32 v60, v60, v61
	v_max_u32_e32 v61, v63, v67
	v_min_u32_e32 v63, v63, v67
	v_max_u32_e32 v67, v152, v10
	v_min_u32_e32 v10, v152, v10
	v_max_u32_e32 v152, v16, v22
	v_min_u32_e32 v16, v16, v22
	v_max_u32_e32 v22, v13, v7
	v_min_u32_e32 v7, v13, v7
	v_max_u32_e32 v13, v4, v1
	v_min_u32_e32 v1, v4, v1
	v_max_u32_e32 v17, v34, v38
	v_min_u32_e32 v34, v34, v38
	v_max_u32_e32 v38, v37, v36
	v_min_u32_e32 v36, v37, v36
	v_max_u32_e32 v37, v32, v33
	v_min_u32_e32 v32, v32, v33
	v_max_u32_e32 v33, v35, v39
	v_min_u32_e32 v35, v35, v39
	v_max_u32_e32 v39, v160, v9
	v_min_u32_e32 v9, v160, v9
	v_max_u32_e32 v160, v15, v21
	v_min_u32_e32 v15, v15, v21
	v_max_u32_e32 v21, v11, v5
	v_min_u32_e32 v5, v11, v5
	v_max_u32_e32 v11, v3, v0
	v_min_u32_e32 v0, v3, v0
	v_min_u32_e32 v26, v30, v46
	v_min_u32_e32 v131, v42, v44
	v_min_u32_e32 v138, v45, v41
	v_min_u32_e32 v139, v40, v43
	v_min_u32_e32 v140, v47, v127
	v_min_u32_e32 v141, v28, v29
	v_min_u32_e32 v142, v31, v27
	v_min_u32_e32 v143, v25, v24
	v_min_u32_e32 v6, v20, v58
	v_min_u32_e32 v145, v54, v56
	v_min_u32_e32 v146, v57, v53
	v_min_u32_e32 v147, v52, v55
	v_min_u32_e32 v148, v59, v144
	v_min_u32_e32 v149, v12, v18
	v_min_u32_e32 v150, v23, v14
	v_min_u32_e32 v151, v8, v2
	v_min_u32_e32 v4, v19, v66
	v_min_u32_e32 v153, v62, v64
	v_min_u32_e32 v154, v65, v61
	v_min_u32_e32 v155, v60, v63
	v_min_u32_e32 v156, v67, v152
	v_min_u32_e32 v157, v10, v16
	v_min_u32_e32 v158, v22, v13
	v_min_u32_e32 v159, v7, v1
	v_min_u32_e32 v3, v17, v38
	v_min_u32_e32 v161, v34, v36
	v_min_u32_e32 v210, v37, v33
	v_min_u32_e32 v211, v32, v35
	v_min_u32_e32 v212, v39, v160
	v_min_u32_e32 v213, v9, v15
	v_min_u32_e32 v214, v21, v11
	v_min_u32_e32 v215, v5, v0
	v_max3_u32 v30, v30, v46, v151
	v_max3_u32 v2, v26, v8, v2
	v_max3_u32 v8, v42, v44, v150
	v_max3_u32 v14, v131, v23, v14
	v_max3_u32 v23, v45, v41, v149
	v_max3_u32 v12, v138, v12, v18
	v_max3_u32 v18, v40, v43, v148
	v_max3_u32 v26, v139, v59, v144
	v_max3_u32 v40, v47, v127, v147
	v_max3_u32 v41, v140, v52, v55
	v_max3_u32 v28, v28, v29, v146
	v_max3_u32 v29, v141, v57, v53
	v_max3_u32 v27, v31, v27, v145
	v_max3_u32 v31, v142, v54, v56
	v_max3_u32 v6, v25, v24, v6
	v_max3_u32 v20, v143, v20, v58
	v_max3_u32 v19, v19, v66, v215
	v_max3_u32 v0, v4, v5, v0
	v_max3_u32 v4, v62, v64, v214
	v_max3_u32 v5, v153, v21, v11
	v_max3_u32 v11, v65, v61, v213
	v_max3_u32 v9, v154, v9, v15
	v_max3_u32 v15, v60, v63, v212
	v_max3_u32 v21, v155, v39, v160
	v_max3_u32 v39, v67, v152, v211
	v_max3_u32 v32, v156, v32, v35
	v_max3_u32 v10, v10, v16, v210
	v_max3_u32 v16, v157, v37, v33
	v_max3_u32 v13, v22, v13, v161
	v_max3_u32 v22, v158, v34, v36
	v_max3_u32 v1, v7, v1, v3
	v_max3_u32 v3, v159, v17, v38
	v_max_u32_e32 v24, v30, v40
	v_min_u32_e32 v25, v30, v40
	v_max_u32_e32 v30, v2, v41
	v_min_u32_e32 v2, v2, v41
	v_max_u32_e32 v40, v8, v28
	v_min_u32_e32 v8, v8, v28
	v_max_u32_e32 v28, v14, v29
	v_min_u32_e32 v14, v14, v29
	v_max_u32_e32 v29, v23, v27
	v_min_u32_e32 v23, v23, v27
	v_max_u32_e32 v27, v12, v31
	v_min_u32_e32 v12, v12, v31
	v_max_u32_e32 v31, v18, v6
	v_min_u32_e32 v6, v18, v6
	v_max_u32_e32 v18, v26, v20
	v_min_u32_e32 v20, v26, v20
	v_max_u32_e32 v7, v19, v39
	v_min_u32_e32 v17, v19, v39
	v_max_u32_e32 v19, v0, v32
	v_min_u32_e32 v0, v0, v32
	v_max_u32_e32 v32, v4, v10
	v_min_u32_e32 v4, v4, v10
	v_max_u32_e32 v10, v5, v16
	v_min_u32_e32 v5, v5, v16
	v_max_u32_e32 v16, v11, v13
	v_min_u32_e32 v11, v11, v13
	v_max_u32_e32 v13, v9, v22
	v_min_u32_e32 v9, v9, v22
	v_max_u32_e32 v22, v15, v1
	v_min_u32_e32 v1, v15, v1
	v_max_u32_e32 v15, v21, v3
	v_min_u32_e32 v3, v21, v3
	v_max_u32_e32 v26, v24, v29
	v_min_u32_e32 v24, v24, v29
	v_max_u32_e32 v29, v30, v27
	v_min_u32_e32 v27, v30, v27
	v_max_u32_e32 v30, v40, v31
	v_min_u32_e32 v31, v40, v31
	v_max_u32_e32 v40, v28, v18
	v_min_u32_e32 v18, v28, v18
	v_max_u32_e32 v28, v25, v23
	v_min_u32_e32 v23, v25, v23
	v_max_u32_e32 v25, v2, v12
	v_min_u32_e32 v2, v2, v12
	v_max_u32_e32 v12, v8, v6
	v_min_u32_e32 v6, v8, v6
	v_max_u32_e32 v8, v14, v20
	v_min_u32_e32 v14, v14, v20
	v_max_u32_e32 v21, v7, v16
	v_min_u32_e32 v7, v7, v16
	v_max_u32_e32 v16, v19, v13
	v_min_u32_e32 v13, v19, v13
	v_max_u32_e32 v19, v32, v22
	v_min_u32_e32 v22, v32, v22
	v_max_u32_e32 v32, v10, v15
	v_min_u32_e32 v10, v10, v15
	v_max_u32_e32 v15, v17, v11
	v_min_u32_e32 v11, v17, v11
	v_max_u32_e32 v17, v0, v9
	v_min_u32_e32 v0, v0, v9
	v_max_u32_e32 v9, v4, v1
	v_min_u32_e32 v1, v4, v1
	v_max_u32_e32 v4, v5, v3
	v_min_u32_e32 v3, v5, v3
	v_max_u32_e32 v20, v26, v30
	v_min_u32_e32 v26, v26, v30
	v_max_u32_e32 v30, v29, v40
	v_min_u32_e32 v29, v29, v40
	v_max_u32_e32 v40, v24, v31
	v_min_u32_e32 v24, v24, v31
	v_max_u32_e32 v31, v27, v18
	v_min_u32_e32 v18, v27, v18
	v_max_u32_e32 v27, v28, v12
	v_min_u32_e32 v12, v28, v12
	v_max_u32_e32 v28, v25, v8
	v_min_u32_e32 v8, v25, v8
	v_max_u32_e32 v25, v23, v6
	v_min_u32_e32 v6, v23, v6
	v_max_u32_e32 v23, v2, v14
	v_min_u32_e32 v2, v2, v14
	v_max_u32_e32 v5, v21, v19
	v_min_u32_e32 v19, v21, v19
	v_max_u32_e32 v21, v16, v32
	v_min_u32_e32 v16, v16, v32
	v_max_u32_e32 v32, v7, v22
	v_min_u32_e32 v7, v7, v22
	v_max_u32_e32 v22, v13, v10
	v_min_u32_e32 v10, v13, v10
	v_max_u32_e32 v13, v15, v9
	v_min_u32_e32 v9, v15, v9
	v_max_u32_e32 v15, v17, v4
	v_min_u32_e32 v4, v17, v4
	v_max_u32_e32 v17, v11, v1
	v_min_u32_e32 v1, v11, v1
	v_max_u32_e32 v11, v0, v3
	v_min_u32_e32 v0, v0, v3
	v_min_u32_e32 v14, v20, v30
	v_min_u32_e32 v41, v26, v29
	v_min_u32_e32 v42, v40, v31
	v_min_u32_e32 v43, v24, v18
	v_min_u32_e32 v44, v27, v28
	v_min_u32_e32 v45, v12, v8
	v_min_u32_e32 v46, v25, v23
	v_min_u32_e32 v47, v6, v2
	v_min_u32_e32 v3, v5, v21
	v_min_u32_e32 v33, v19, v16
	v_min_u32_e32 v34, v32, v22
	v_min_u32_e32 v35, v7, v10
	v_min_u32_e32 v36, v13, v15
	v_min_u32_e32 v37, v9, v4
	v_min_u32_e32 v38, v17, v11
	v_min_u32_e32 v39, v1, v0
	v_max3_u32 v20, v20, v30, v39
	v_max3_u32 v0, v14, v1, v0
	v_max3_u32 v1, v26, v29, v38
	v_max3_u32 v11, v41, v17, v11
	v_max3_u32 v14, v40, v31, v37
	v_max3_u32 v4, v42, v9, v4
	v_max3_u32 v9, v24, v18, v36
	v_max3_u32 v13, v43, v13, v15
	v_max3_u32 v15, v27, v28, v35
	v_max3_u32 v7, v44, v7, v10
	v_max3_u32 v8, v12, v8, v34
	v_max3_u32 v10, v45, v32, v22
	v_max3_u32 v12, v25, v23, v33
	v_max3_u32 v16, v46, v19, v16
	v_max3_u32 v2, v6, v2, v3
	v_max3_u32 v3, v47, v5, v21
	v_max_u32_e32 v5, v20, v15
	v_min_u32_e32 v6, v20, v15
	v_max_u32_e32 v15, v0, v7
	v_min_u32_e32 v0, v0, v7
	v_max_u32_e32 v7, v1, v8
	v_min_u32_e32 v1, v1, v8
	v_max_u32_e32 v8, v11, v10
	v_min_u32_e32 v10, v11, v10
	v_max_u32_e32 v11, v14, v12
	v_min_u32_e32 v12, v14, v12
	v_max_u32_e32 v14, v4, v16
	v_min_u32_e32 v4, v4, v16
	v_max_u32_e32 v16, v9, v2
	v_min_u32_e32 v2, v9, v2
	v_max_u32_e32 v9, v13, v3
	v_min_u32_e32 v3, v13, v3
	v_max_u32_e32 v13, v5, v11
	v_min_u32_e32 v5, v5, v11
	v_max_u32_e32 v11, v15, v14
	v_min_u32_e32 v14, v15, v14
	v_max_u32_e32 v15, v7, v16
	v_min_u32_e32 v7, v7, v16
	v_max_u32_e32 v16, v8, v9
	v_min_u32_e32 v8, v8, v9
	v_max_u32_e32 v9, v6, v12
	v_min_u32_e32 v6, v6, v12
	v_max_u32_e32 v12, v0, v4
	v_min_u32_e32 v0, v0, v4
	v_max_u32_e32 v4, v1, v2
	v_min_u32_e32 v1, v1, v2
	v_max_u32_e32 v2, v10, v3
	v_min_u32_e32 v3, v10, v3
	v_max_u32_e32 v10, v13, v15
	v_min_u32_e32 v15, v13, v15
	v_max_u32_e32 v13, v11, v16
	v_min_u32_e32 v11, v11, v16
	v_max_u32_e32 v16, v5, v7
	v_min_u32_e32 v5, v5, v7
	v_max_u32_e32 v7, v14, v8
	v_min_u32_e32 v17, v14, v8
	v_max_u32_e32 v18, v9, v4
	v_min_u32_e32 v19, v9, v4
	v_max_u32_e32 v20, v12, v2
	v_min_u32_e32 v2, v12, v2
	v_max_u32_e32 v21, v6, v1
	v_min_u32_e32 v22, v6, v1
	v_max_u32_e32 v1, v0, v3
	v_min_u32_e32 v3, v0, v3
	v_max_u32_e32 v12, v10, v13
	v_min_u32_e32 v13, v10, v13
	v_max_u32_e32 v14, v15, v11
	v_min_u32_e32 v15, v15, v11
	v_max_u32_e32 v8, v16, v7
	v_min_u32_e32 v9, v16, v7
	v_max_u32_e32 v10, v5, v17
	v_min_u32_e32 v11, v5, v17
	v_max_u32_e32 v4, v18, v20
	v_min_u32_e32 v5, v18, v20
	v_max_u32_e32 v6, v19, v2
	v_min_u32_e32 v7, v19, v2
	v_max_u32_e32 v0, v21, v1
	v_min_u32_e32 v1, v21, v1
	v_max_u32_e32 v2, v22, v3
	v_min_u32_e32 v3, v22, v3
	s_and_saveexec_b64 s[34:35], s[40:41]
	s_cbranch_execz .LBB0_83
	ds_write_b128 v132, v[12:15]
	ds_write_b128 v132, v[8:11] offset:16
	ds_write_b128 v132, v[4:7] offset:32
	ds_write_b128 v132, v[0:3] offset:48
